# indexer phase: one static s_setprio 1 for waves 4-7 (two waves per SIMD), reset to 0 at the phase's closing barrier
# baseline (speedup 1.0000x reference)
; __device__ __forceinline__ int fresh_tid() { int t = threadIdx.x; asm volatile("" : "+v"(t)); return t; }
; #define LAS __attribute__((address_space(3)))
; __device__ __forceinline__ void indexer_phase(const bf16_t* PJ, float* rk, unsigned short* SEL, LAS unsigned char* lds) {
;     const int tid = fresh_tid(), lane = tid & 63, r32 = lane & 31, hi = lane >> 5;
;     const int wid = __builtin_amdgcn_readfirstlane(tid >> 6);
;     { const int gw = blockIdx.x * NWAVE + wid, NGW = gridDim.x * NWAVE;
;       for (int t4 = gw; t4 < TOK / 4; t4 += NGW) { const int tok = 4 * t4 + (lane >> 4);
;           const u32x4 w = *(const u32x4*)(PJ + (size_t)tok * PROJ_LD + PJ_LAT + 8 * (lane & 15));
;           float ss = bflo(w.x) * bflo(w.x) + bfhi(w.x) * bfhi(w.x) + bflo(w.y) * bflo(w.y) + bfhi(w.y) * bfhi(w.y) + bflo(w.z) * bflo(w.z) + bfhi(w.z) * bfhi(w.z) + bflo(w.w) * bflo(w.w) + bfhi(w.w) * bfhi(w.w);
;           ss += __shfl_xor(ss, 1); ss += __shfl_xor(ss, 2); ss += __shfl_xor(ss, 4); ss += __shfl_xor(ss, 8);
;           if ((lane & 15) == 0) rk[tok] = rsqrtf(ss * (1.f / 128.f) + RMS_EPS); } }
;     constexpr int AUX0 = 131072, AUXW = 3072;
;     LAS unsigned* hist = (LAS unsigned*)(lds + AUX0 + wid * AUXW);
;     LAS unsigned short* listA = (LAS unsigned short*)(lds + AUX0 + wid * AUXW + 2080);
;     LAS float* pmm = (LAS float*)(lds + AUX0 + NWAVE * AUXW);
.LBB0_861:
	s_cmpk_gt_i32 s76, 0xfff
	s_cbranch_scc1 .LBB0_1030
	v_writelane_b32 v255, s60, 15
	s_mul_i32 s0, s33, 0xc00
	s_add_i32 s94, s0, 0
	v_writelane_b32 v255, s61, 16
	v_writelane_b32 v255, s59, 17
	s_add_i32 s94, s94, 0x20000
	v_writelane_b32 v255, s82, 18
	s_add_u32 s4, s10, 0x1e400000
	s_addc_u32 s5, s11, 0
	v_writelane_b32 v255, s83, 19
	s_lshl_b32 s0, s33, 5
	s_mul_i32 s2, s33, 0x2c000
	v_writelane_b32 v255, s0, 20
	s_mul_hi_i32 s3, s0, 0x1600
	v_lshrrev_b32_e32 v1, 5, v108
	v_writelane_b32 v255, s2, 21
	v_lshrrev_b32_e32 v2, 1, v6
	v_bfe_u32 v3, v6, 4, 1
	v_lshlrev_b32_e32 v116, 1, v1
	v_writelane_b32 v255, s3, 22
	s_lshl_b32 s0, s33, 3
	v_and_or_b32 v112, v2, 2, v3
	v_writelane_b32 v255, s0, 23
	v_or_b32_e32 v3, s0, v116
	s_lshl_b32 s0, s33, 14
	s_add_i32 s96, s0, 0
	v_mov_b32_e32 v4, 0x200
	v_lshl_add_u32 v119, v108, 5, s94
	s_movk_i32 s0, 0xffe4
	v_and_b32_e32 v0, 3, v6
	v_and_or_b32 v113, v6, 7, v4
	v_mad_i32_i24 v158, v108, s0, v119
	v_or_b32_e32 v4, 0x200, v108
	s_movk_i32 s0, 0x208
	v_and_or_b32 v0, v2, 4, v0
	v_cmp_gt_u32_e64 s[10:11], s0, v4
	s_lshl_b32 s0, s33, 7
	v_and_b32_e32 v110, 31, v6
	v_lshlrev_b32_e32 v0, 6, v0
	v_lshlrev_b32_e32 v2, 3, v1
	v_lshlrev_b32_e32 v118, 2, v108
	v_lshl_add_u32 v1, v1, 15, s0
	v_lshlrev_b32_e32 v117, 3, v108
	v_add_u32_e32 v159, v158, v118
	v_lshlrev_b32_e32 v160, 3, v3
	v_sub_u32_e32 v3, 0, v118
	v_lshl_or_b32 v1, v110, 2, v1
	v_lshlrev_b32_e32 v114, 1, v0
	v_mbcnt_hi_u32_b32 v180, -1, v195
	v_mov_b32_e32 v0, 0x80
	v_mov_b32_e32 v115, 0
	s_movk_i32 s7, 0x1600
	v_cmp_eq_u32_e64 s[8:9], 0, v110
	v_lshl_add_u32 v111, v108, 4, s96
	v_or_b32_e32 v121, 0x100, v108
	v_or_b32_e32 v120, 1, v116
	v_cmp_eq_u32_e64 s[12:13], 63, v108
	v_cmp_gt_u32_e64 s[14:15], 62, v108
	v_cmp_gt_u32_e64 s[16:17], 60, v108
	v_cmp_gt_u32_e64 s[18:19], 56, v108
	v_cmp_gt_u32_e64 s[20:21], 48, v108
	v_cmp_gt_u32_e64 s[22:23], 32, v108
	v_or_b32_e32 v161, 7, v117
	v_or_b32_e32 v162, 6, v117
	v_or_b32_e32 v163, 5, v117
	v_or_b32_e32 v164, 4, v117
	v_or_b32_e32 v165, 3, v117
	v_or_b32_e32 v166, 2, v117
	v_or_b32_e32 v167, 1, v117
	v_or_b32_e32 v168, 64, v108
	v_or_b32_e32 v169, 0x80, v108
	v_or_b32_e32 v170, 0xc0, v108
	v_mov_b32_e32 v109, v108
	v_add_u32_e32 v171, 0, v1
	v_or_b32_e32 v172, 0x100, v118
	v_add_u32_e32 v173, s96, v118
	v_lshlrev_b32_e32 v122, 1, v2
	s_movk_i32 s44, 0x1000
	s_mov_b32 s58, 0x3eb504f3
	s_mov_b32 s45, 0x43ff8000
	v_mov_b32_e32 v174, 1
	v_lshlrev_b32_e32 v175, 1, v118
	v_lshlrev_b32_e32 v176, 1, v108
	v_mov_b32_e32 v177, 0x1600
	v_mov_b32_e32 v178, 0xff800000
	v_mov_b32_e32 v179, 0x7f800000
	v_lshl_or_b32 v181, v180, 2, v0
	v_add_u32_e32 v182, v159, v3
	s_mov_b32 s2, s76
	v_lshrrev_b32_e32 v222, 2, v108
	v_and_b32_e32 v223, 31, v108
	v_sub_u32_e32 v218, v222, v223
	v_mul_i32_i24_e32 v218, 0x1600, v218
	v_and_b32_e32 v224, 3, v108
	v_lshrrev_b32_e32 v225, 5, v108
	v_sub_u32_e32 v219, v224, v225
	v_lshl_add_u32 v218, v219, 4, v218
	v_ashrrev_i32_e32 v219, 31, v218
	v_bfe_u32 v226, v108, 4, 2
	v_xor_b32_e32 v226, v224, v226
	v_lshlrev_b32_e32 v226, 4, v226
	v_lshl_add_u32 v222, v222, 6, v226
	v_add_u32_e32 v222, s94, v222
	v_bfe_u32 v226, v108, 2, 2
	v_xor_b32_e32 v226, v225, v226
	v_lshlrev_b32_e32 v226, 4, v226
	v_lshl_add_u32 v223, v223, 6, v226
	v_add_u32_e32 v223, s94, v223
	v_xor_b32_e32 v224, 32, v223
	s_cmp_lt_u32 s33, 4
	s_cbranch_scc1 .Lidx_noprio
	s_setprio 1

; __device__ __forceinline__ unsigned xb_ld(unsigned* p)              { return __hip_atomic_load(p, __ATOMIC_RELAXED, __HIP_MEMORY_SCOPE_AGENT); }
; __device__ __forceinline__ void xcd_barrier_complete(unsigned* bar, unsigned x, unsigned& nloc, unsigned& nx) {
;     const unsigned G = gridDim.x * gridDim.y * gridDim.z;
;     unsigned sum, cnt, mine, sp = 0u;
;     for (;;) {
;         sum = 0u; cnt = 0u; mine = 0u;
; #pragma unroll
;         for (unsigned j = 0; j < 16; ++j) { const unsigned c = xb_ld(&bar[XB_XCNT(j)]); sum += c; cnt += (c > 0u) ? 1u : 0u; mine = (j == x) ? c : mine; }
; __device__ __forceinline__ void xcd_barrier(const XcdBarrier& b) {
;     asm volatile("s_waitcnt vmcnt(0)" ::: "memory");
;     __syncthreads();
;     if (threadIdx.x == 0) {
;         unsigned* bar = b.bar;
;         __builtin_amdgcn_s_waitcnt(0);
;         unsigned nloc = b.st[0], nx = b.st[1];
;         if (nloc == 0u) { xcd_barrier_complete(bar, b.x, nloc, nx); b.st[0] = nloc; b.st[1] = nx; }
.LBB0_1030:
	s_setprio 0
	s_waitcnt vmcnt(0)
	s_waitcnt lgkmcnt(0)
	s_barrier
	s_mov_b64 s[8:9], exec
	v_readlane_b32 s0, v255, 6
	v_readlane_b32 s1, v255, 7
	s_and_b64 s[0:1], s[8:9], s[0:1]
	s_mov_b64 exec, s[0:1]
	s_cbranch_execz .LBB0_1082
	s_add_i32 s0, 0, 0x26200
	v_mov_b32_e32 v0, s0
	s_waitcnt vmcnt(0) expcnt(0) lgkmcnt(0)
	ds_read_b32 v2, v0
	s_add_i32 s0, 0, 0x26204
	v_mov_b32_e32 v0, s0
	ds_read_b32 v0, v0
	s_waitcnt lgkmcnt(1)
	v_cmp_ne_u32_e32 vcc, 0, v2
	s_cbranch_vccnz .LBB0_1046
	v_readlane_b32 s2, v255, 1
	v_readlane_b32 s3, v255, 2
	s_add_u32 s10, s2, 0x180200
	s_addc_u32 s11, s3, 0
	s_add_u32 s12, s2, 0x180400
	s_addc_u32 s13, s3, 0
	s_add_u32 s14, s2, 0x180500
	s_addc_u32 s15, s3, 0
	s_add_u32 s16, s2, 0x180600
	s_addc_u32 s17, s3, 0
	s_add_u32 s18, s2, 0x180700
	s_addc_u32 s19, s3, 0
	s_add_u32 s20, s2, 0x180800
	s_addc_u32 s21, s3, 0
	s_add_u32 s22, s2, 0x180900
	s_addc_u32 s23, s3, 0
	s_add_u32 s24, s2, 0x180a00
	s_addc_u32 s25, s3, 0
	s_add_u32 s26, s2, 0x180b00
	s_addc_u32 s27, s3, 0
	s_add_u32 s28, s2, 0x180c00
	s_addc_u32 s29, s3, 0
	s_add_u32 s30, s2, 0x180d00
	s_addc_u32 s31, s3, 0
	s_add_u32 s34, s2, 0x180e00
	s_addc_u32 s35, s3, 0
	s_add_u32 s36, s2, 0x180f00
	s_addc_u32 s37, s3, 0
	s_add_u32 s38, s2, 0x181000
	s_addc_u32 s39, s3, 0
	s_add_u32 s40, s2, 0x181100
	s_addc_u32 s41, s3, 0
	s_add_u32 s42, s2, 0x181200
	v_readlane_b32 s0, v255, 0
	s_addc_u32 s43, s3, 0
	s_mul_i32 s0, s73, s0
	s_add_u32 s46, s2, 0x181300
	s_mul_i32 s0, s0, s72
	s_addc_u32 s47, s3, 0
	s_mov_b32 s1, 1
	v_mov_b32_e32 v16, 0
	s_branch .LBB0_1034
